# combo + nsa selected-attention tile mask rewritten (2 VALU/element via per-lane threshold compare)
# speedup vs baseline: 1.0008x; 1.0008x over previous
; DI int crow(int r, int hi) { return (r & 3) + 8 * (r >> 2) + 4 * hi; }
; template <class MaskF>
; DI void attn_tile(const int tid, const char* ldsK, const char* ldsV, const bf16x8 (&qr)[4], f32x16 (&o)[2], float& m, float& l, const bool MASKED, MaskF mask) {
;     ...
;   if (MASKED) {
; #pragma unroll
;     for (int r = 0; r < 16; ++r) {
;       const int kr = crow(r, hi);
;       p0[r] = mask(kr) ? p0[r] : NEGB; p1[r] = mask(kr + 32) ? p1[r] : NEGB;
;     }
; DI void nsa_item(const Params& p, int it, char* lds) {
;     ...
;   attn_stream(tid, proj, C_KSLC, C_VSLC, __builtin_popcount(anym),
;               [&](int ti, int row) { return b * S_ + jlist[ti] * 64 + row; },
;               [&](int ti) { const int jb = jlist[ti]; return (jb < cur) && ((allm >> jb) & 1u); },
;               [&](int ti, int kr) { const int jb = jlist[ti]; return ((mymask >> jb) & 1u) && (jb * 64 + kr <= t); },
;               qr, o, m, lsum, lds);
.LBB0_475:
	ds_read_b128 v[32:35], v219
	ds_read_b128 v[112:115], v219 offset:32
	ds_read_b128 v[124:127], v219 offset:4608
	ds_read_b128 v[116:119], v219 offset:96
	ds_read_b128 v[128:131], v219 offset:4640
	ds_read_b128 v[132:135], v219 offset:64
	ds_read_b128 v[136:139], v219 offset:4672
	ds_read_b128 v[140:143], v219 offset:4704
	v_mov_b32_e32 v120, s5
	s_waitcnt lgkmcnt(7)
	v_mfma_f32_32x32x16_bf16 v[48:63], v[32:35], v[64:67], 0
	s_waitcnt lgkmcnt(6)
	v_mfma_f32_32x32x16_bf16 v[48:63], v[112:115], v[68:71], v[48:63]
	s_waitcnt lgkmcnt(5)
	v_mfma_f32_32x32x16_bf16 v[32:47], v[124:127], v[64:67], 0
	s_waitcnt lgkmcnt(3)
	v_mfma_f32_32x32x16_bf16 v[32:47], v[128:131], v[68:71], v[32:47]
	s_waitcnt lgkmcnt(2)
	v_mfma_f32_32x32x16_bf16 v[48:63], v[132:135], v[72:75], v[48:63]
	s_waitcnt lgkmcnt(1)
	v_mfma_f32_32x32x16_bf16 v[32:47], v[136:139], v[72:75], v[32:47]
	ds_read_b32 v112, v120
	s_waitcnt lgkmcnt(0)
	v_lshlrev_b32_e64 v113, v112, 1
	v_and_b32_e32 v114, s2, v113
	v_mfma_f32_32x32x16_bf16 v[48:63], v[116:119], v[76:79], v[48:63]
	v_cmp_le_i32_e32 vcc, s36, v112
	v_cmp_eq_u32_e64 s[0:1], 0, v114
	s_or_b64 s[0:1], vcc, s[0:1]
	s_andn2_b64 vcc, exec, s[0:1]
	v_mfma_f32_32x32x16_bf16 v[32:47], v[140:143], v[76:79], v[32:47]
	s_cbranch_vccnz .LBB0_477
	v_and_b32_e32 v113, v113, v166
	v_lshlrev_b32_e32 v112, 6, v112
	v_cmp_ne_u32_e32 vcc, 0, v113
	v_sub_u32_e32 v113, v147, v112
	s_nop 0
	v_cndmask_b32_e32 v113, -1, v113, vcc
	v_cmp_ge_i32_e64 s[0:1], v113, v156
	v_cmp_ge_i32_e64 s[10:11], v113, v157
	v_cmp_ge_i32_e64 s[12:13], v113, v160
	v_cndmask_b32_e64 v48, v194, v48, s[0:1]
	v_cmp_ge_i32_e64 s[0:1], v113, v168
	v_cndmask_b32_e64 v32, v194, v32, s[10:11]
	v_cmp_ge_i32_e64 s[10:11], v113, v169
	v_cndmask_b32_e64 v49, v194, v49, s[12:13]
	v_cmp_ge_i32_e64 s[12:13], v113, v170
	v_cndmask_b32_e64 v33, v194, v33, s[0:1]
	v_cmp_ge_i32_e64 s[0:1], v113, v171
	v_cndmask_b32_e64 v50, v194, v50, s[10:11]
	v_cmp_ge_i32_e64 s[10:11], v113, v172
	v_cndmask_b32_e64 v34, v194, v34, s[12:13]
	v_cmp_ge_i32_e64 s[12:13], v113, v173
	v_cndmask_b32_e64 v51, v194, v51, s[0:1]
	v_cmp_ge_i32_e64 s[0:1], v113, v174
	v_cndmask_b32_e64 v35, v194, v35, s[10:11]
	v_cmp_ge_i32_e64 s[10:11], v113, v175
	v_cndmask_b32_e64 v52, v194, v52, s[12:13]
	v_cmp_ge_i32_e64 s[12:13], v113, v181
	v_cndmask_b32_e64 v36, v194, v36, s[0:1]
	v_cmp_ge_i32_e64 s[0:1], v113, v183
	v_cndmask_b32_e64 v53, v194, v53, s[10:11]
	v_cmp_ge_i32_e64 s[10:11], v113, v185
	v_cndmask_b32_e64 v37, v194, v37, s[12:13]
	v_cmp_ge_i32_e64 s[12:13], v113, v186
	v_cndmask_b32_e64 v54, v194, v54, s[0:1]
	v_cmp_ge_i32_e64 s[0:1], v113, v187
	v_cndmask_b32_e64 v38, v194, v38, s[10:11]
	v_cmp_ge_i32_e64 s[10:11], v113, v202
	v_cndmask_b32_e64 v55, v194, v55, s[12:13]
	v_cmp_ge_i32_e64 s[12:13], v113, v203
	v_cndmask_b32_e64 v39, v194, v39, s[0:1]
	v_cmp_ge_i32_e64 s[0:1], v113, v204
	v_cndmask_b32_e64 v56, v194, v56, s[10:11]
	v_cmp_ge_i32_e64 s[10:11], v113, v205
	v_cndmask_b32_e64 v40, v194, v40, s[12:13]
	v_cmp_ge_i32_e64 s[12:13], v113, v206
	v_cndmask_b32_e64 v57, v194, v57, s[0:1]
	v_cmp_ge_i32_e64 s[0:1], v113, v207
	v_cndmask_b32_e64 v41, v194, v41, s[10:11]
	v_cmp_ge_i32_e64 s[10:11], v113, v208
	v_cndmask_b32_e64 v58, v194, v58, s[12:13]
	v_cmp_ge_i32_e64 s[12:13], v113, v209
	v_cndmask_b32_e64 v42, v194, v42, s[0:1]
	v_cmp_ge_i32_e64 s[0:1], v113, v210
	v_cndmask_b32_e64 v59, v194, v59, s[10:11]
	v_cmp_ge_i32_e64 s[10:11], v113, v211
	v_cndmask_b32_e64 v43, v194, v43, s[12:13]
	v_cmp_ge_i32_e64 s[12:13], v113, v212
	v_cndmask_b32_e64 v60, v194, v60, s[0:1]
	v_cmp_ge_i32_e64 s[0:1], v113, v213
	v_cndmask_b32_e64 v44, v194, v44, s[10:11]
	v_cmp_ge_i32_e64 s[10:11], v113, v214
	v_cndmask_b32_e64 v61, v194, v61, s[12:13]
	v_cmp_ge_i32_e64 s[12:13], v113, v215
	v_cndmask_b32_e64 v45, v194, v45, s[0:1]
	v_cmp_ge_i32_e64 s[0:1], v113, v216
	v_cndmask_b32_e64 v62, v194, v62, s[10:11]
	v_cmp_ge_i32_e64 s[10:11], v113, v217
	v_cndmask_b32_e64 v46, v194, v46, s[12:13]
	v_cndmask_b32_e64 v63, v194, v63, s[0:1]
	v_cndmask_b32_e64 v47, v194, v47, s[10:11]

; DI int crow(int r, int hi) { return (r & 3) + 8 * (r >> 2) + 4 * hi; }
; template <class MaskF>
; DI void attn_tile(const int tid, const char* ldsK, const char* ldsV, const bf16x8 (&qr)[4], f32x16 (&o)[2], float& m, float& l, const bool MASKED, MaskF mask) {
;     ...
;   if (MASKED) {
; #pragma unroll
;     for (int r = 0; r < 16; ++r) {
;       const int kr = crow(r, hi);
;       p0[r] = mask(kr) ? p0[r] : NEGB; p1[r] = mask(kr + 32) ? p1[r] : NEGB;
;     }
; DI void nsa_item(const Params& p, int it, char* lds) {
;     ...
;   attn_stream(tid, proj, C_KSLC, C_VSLC, __builtin_popcount(anym),
;               [&](int ti, int row) { return b * S_ + jlist[ti] * 64 + row; },
;               [&](int ti) { const int jb = jlist[ti]; return (jb < cur) && ((allm >> jb) & 1u); },
;               [&](int ti, int kr) { const int jb = jlist[ti]; return ((mymask >> jb) & 1u) && (jb * 64 + kr <= t); },
;               qr, o, m, lsum, lds);
.LBB0_482:
	ds_read_b128 v[32:35], v219 offset:18432
	ds_read_b128 v[112:115], v219 offset:18464
	ds_read_b128 v[124:127], v219 offset:23040
	ds_read_b128 v[116:119], v219 offset:18528
	ds_read_b128 v[128:131], v219 offset:23072
	ds_read_b128 v[132:135], v219 offset:18496
	ds_read_b128 v[136:139], v219 offset:23104
	ds_read_b128 v[140:143], v219 offset:23136
	v_mov_b32_e32 v120, s5
	s_waitcnt lgkmcnt(7)
	v_mfma_f32_32x32x16_bf16 v[48:63], v[32:35], v[64:67], 0
	s_waitcnt lgkmcnt(6)
	v_mfma_f32_32x32x16_bf16 v[48:63], v[112:115], v[68:71], v[48:63]
	s_waitcnt lgkmcnt(5)
	v_mfma_f32_32x32x16_bf16 v[32:47], v[124:127], v[64:67], 0
	s_waitcnt lgkmcnt(3)
	v_mfma_f32_32x32x16_bf16 v[32:47], v[128:131], v[68:71], v[32:47]
	s_waitcnt lgkmcnt(2)
	v_mfma_f32_32x32x16_bf16 v[48:63], v[132:135], v[72:75], v[48:63]
	s_waitcnt lgkmcnt(1)
	v_mfma_f32_32x32x16_bf16 v[32:47], v[136:139], v[72:75], v[32:47]
	ds_read_b32 v112, v120 offset:4
	s_waitcnt lgkmcnt(0)
	v_lshlrev_b32_e64 v113, v112, 1
	v_and_b32_e32 v114, s2, v113
	v_mfma_f32_32x32x16_bf16 v[48:63], v[116:119], v[76:79], v[48:63]
	v_cmp_le_i32_e32 vcc, s36, v112
	v_cmp_eq_u32_e64 s[0:1], 0, v114
	s_or_b64 s[0:1], vcc, s[0:1]
	s_andn2_b64 vcc, exec, s[0:1]
	v_mfma_f32_32x32x16_bf16 v[32:47], v[140:143], v[76:79], v[32:47]
	s_cbranch_vccnz .LBB0_484
	v_and_b32_e32 v113, v113, v166
	v_lshlrev_b32_e32 v112, 6, v112
	v_cmp_ne_u32_e32 vcc, 0, v113
	v_sub_u32_e32 v113, v147, v112
	s_nop 0
	v_cndmask_b32_e32 v113, -1, v113, vcc
	v_cmp_ge_i32_e64 s[0:1], v113, v156
	v_cmp_ge_i32_e64 s[10:11], v113, v157
	v_cmp_ge_i32_e64 s[12:13], v113, v160
	v_cndmask_b32_e64 v48, v194, v48, s[0:1]
	v_cmp_ge_i32_e64 s[0:1], v113, v168
	v_cndmask_b32_e64 v32, v194, v32, s[10:11]
	v_cmp_ge_i32_e64 s[10:11], v113, v169
	v_cndmask_b32_e64 v49, v194, v49, s[12:13]
	v_cmp_ge_i32_e64 s[12:13], v113, v170
	v_cndmask_b32_e64 v33, v194, v33, s[0:1]
	v_cmp_ge_i32_e64 s[0:1], v113, v171
	v_cndmask_b32_e64 v50, v194, v50, s[10:11]
	v_cmp_ge_i32_e64 s[10:11], v113, v172
	v_cndmask_b32_e64 v34, v194, v34, s[12:13]
	v_cmp_ge_i32_e64 s[12:13], v113, v173
	v_cndmask_b32_e64 v51, v194, v51, s[0:1]
	v_cmp_ge_i32_e64 s[0:1], v113, v174
	v_cndmask_b32_e64 v35, v194, v35, s[10:11]
	v_cmp_ge_i32_e64 s[10:11], v113, v175
	v_cndmask_b32_e64 v52, v194, v52, s[12:13]
	v_cmp_ge_i32_e64 s[12:13], v113, v181
	v_cndmask_b32_e64 v36, v194, v36, s[0:1]
	v_cmp_ge_i32_e64 s[0:1], v113, v183
	v_cndmask_b32_e64 v53, v194, v53, s[10:11]
	v_cmp_ge_i32_e64 s[10:11], v113, v185
	v_cndmask_b32_e64 v37, v194, v37, s[12:13]
	v_cmp_ge_i32_e64 s[12:13], v113, v186
	v_cndmask_b32_e64 v54, v194, v54, s[0:1]
	v_cmp_ge_i32_e64 s[0:1], v113, v187
	v_cndmask_b32_e64 v38, v194, v38, s[10:11]
	v_cmp_ge_i32_e64 s[10:11], v113, v202
	v_cndmask_b32_e64 v55, v194, v55, s[12:13]
	v_cmp_ge_i32_e64 s[12:13], v113, v203
	v_cndmask_b32_e64 v39, v194, v39, s[0:1]
	v_cmp_ge_i32_e64 s[0:1], v113, v204
	v_cndmask_b32_e64 v56, v194, v56, s[10:11]
	v_cmp_ge_i32_e64 s[10:11], v113, v205
	v_cndmask_b32_e64 v40, v194, v40, s[12:13]
	v_cmp_ge_i32_e64 s[12:13], v113, v206
	v_cndmask_b32_e64 v57, v194, v57, s[0:1]
	v_cmp_ge_i32_e64 s[0:1], v113, v207
	v_cndmask_b32_e64 v41, v194, v41, s[10:11]
	v_cmp_ge_i32_e64 s[10:11], v113, v208
	v_cndmask_b32_e64 v58, v194, v58, s[12:13]
	v_cmp_ge_i32_e64 s[12:13], v113, v209
	v_cndmask_b32_e64 v42, v194, v42, s[0:1]
	v_cmp_ge_i32_e64 s[0:1], v113, v210
	v_cndmask_b32_e64 v59, v194, v59, s[10:11]
	v_cmp_ge_i32_e64 s[10:11], v113, v211
	v_cndmask_b32_e64 v43, v194, v43, s[12:13]
	v_cmp_ge_i32_e64 s[12:13], v113, v212
	v_cndmask_b32_e64 v60, v194, v60, s[0:1]
	v_cmp_ge_i32_e64 s[0:1], v113, v213
	v_cndmask_b32_e64 v44, v194, v44, s[10:11]
	v_cmp_ge_i32_e64 s[10:11], v113, v214
	v_cndmask_b32_e64 v61, v194, v61, s[12:13]
	v_cmp_ge_i32_e64 s[12:13], v113, v215
	v_cndmask_b32_e64 v45, v194, v45, s[0:1]
	v_cmp_ge_i32_e64 s[0:1], v113, v216
	v_cndmask_b32_e64 v62, v194, v62, s[10:11]
	v_cmp_ge_i32_e64 s[10:11], v113, v217
	v_cndmask_b32_e64 v46, v194, v46, s[12:13]
	v_cndmask_b32_e64 v63, v194, v63, s[0:1]
	v_cndmask_b32_e64 v47, v194, v47, s[10:11]
